# input rmsnorm phase row loop: gain and scale vector loads of the 4 column groups issued as one batch per row (gain vectors fetched once per trip) instead of one load-wait pair per group
# speedup vs baseline: 1.0196x; 1.0086x over previous
; __device__ __forceinline__ unsigned pk2(float lo, float hi) { return f2bf(lo) | (f2bf(hi) << 16); }
; __device__ __forceinline__ void phase_xs(Ctx& F, const float* xlat, const float* xctx, const float* g, const float* modl, float* ss1, bf16* XS) {
;     ...
;         for (int q = 0; q < 2; ++q) { const int row = row0 + q; const int s = row < ML ? (row >> 13) : 4;
;             const float* sc = modl + s * MODW + DM;
; #pragma unroll
;             for (int j = 0; j < 4; ++j) ss[q] += (v[q][j][0] * v[q][j][0] + v[q][j][1] * v[q][j][1]) + (v[q][j][2] * v[q][j][2] + v[q][j][3] * v[q][j][3]);
;             ss[q] = wave_sum(ss[q]);
;             if (lane == 0) ss1[row] = ss[q];
; #pragma unroll
;             for (int j = 0; j < 4; ++j) { const int c = 256 * j + 4 * lane;
;                 const f32x4 gg = *(const f32x4*)(g + c), s1 = *(const f32x4*)(sc + c);
;                 const f32x4 y = v[q][j] * gg * (s1 + 1.0f);
;                 v2u w; w.x = pk2(y[0], y[1]); w.y = pk2(y[2], y[3]); *(v2u*)(XS + (size_t)row * DM + c) = w; } }
.LBB0_36:
	s_or_b64 exec, exec, s[0:1]
	s_and_b64 s[0:1], s[12:13], exec
	s_cselect_b32 s0, s20, 0x6000
	s_ashr_i32 s1, s0, 31
	s_lshl_b64 s[0:1], s[0:1], 2
	s_add_u32 s0, s62, s0
	s_addc_u32 s1, s63, s1
	s_add_u32 s0, s0, 0x1000
	s_addc_u32 s1, s1, 0
	global_load_dwordx4 v[128:131], v44, s[0:1]
	global_load_dwordx4 v[132:135], v45, s[0:1]
	global_load_dwordx4 v[136:139], v46, s[0:1]
	global_load_dwordx4 v[140:143], v47, s[0:1]
	s_waitcnt lgkmcnt(0)
	s_add_u32 s4, s4, s2
	s_addc_u32 s5, s5, s3
	s_add_u32 s6, s6, s8
	s_addc_u32 s7, s7, s9
	s_cmp_lt_i32 s4, 0x8400
	v_lshl_add_u64 v[34:35], v[34:35], 0, s[10:11]
	s_waitcnt vmcnt(3)
	v_pk_mul_f32 v[14:15], v[14:15], v[98:99]
	v_pk_mul_f32 v[12:13], v[12:13], v[96:97]
	v_pk_add_f32 v[16:17], v[130:131], 1.0 op_sel_hi:[1, 0]
	v_pk_add_f32 v[18:19], v[128:129], 1.0 op_sel_hi:[1, 0]
	v_pk_mul_f32 v[14:15], v[14:15], v[16:17]
	v_pk_mul_f32 v[12:13], v[12:13], v[18:19]
	v_bfe_u32 v18, v14, 16, 1
	v_bfe_u32 v16, v12, 16, 1
	v_bfe_u32 v17, v13, 16, 1
	v_bfe_u32 v19, v15, 16, 1
	v_add3_u32 v12, v12, v16, s75
	v_add3_u32 v14, v14, v18, s75
	v_add3_u32 v13, v13, v17, s75
	v_add3_u32 v15, v15, v19, s75
	v_lshrrev_b32_e32 v12, 16, v12
	v_lshrrev_b32_e32 v14, 16, v14
	v_and_or_b32 v12, v13, s95, v12
	v_and_or_b32 v13, v15, s95, v14
	global_store_dwordx2 v[36:37], v[12:13], off offset:2048
	s_waitcnt vmcnt(2)
	v_pk_mul_f32 v[10:11], v[10:11], v[102:103]
	v_pk_mul_f32 v[8:9], v[8:9], v[100:101]
	v_pk_add_f32 v[12:13], v[134:135], 1.0 op_sel_hi:[1, 0]
	v_pk_add_f32 v[14:15], v[132:133], 1.0 op_sel_hi:[1, 0]
	v_pk_mul_f32 v[10:11], v[10:11], v[12:13]
	v_pk_mul_f32 v[8:9], v[8:9], v[14:15]
	v_bfe_u32 v14, v10, 16, 1
	v_bfe_u32 v12, v8, 16, 1
	v_bfe_u32 v13, v9, 16, 1
	v_bfe_u32 v15, v11, 16, 1
	v_add3_u32 v8, v8, v12, s75
	v_add3_u32 v10, v10, v14, s75
	v_add3_u32 v9, v9, v13, s75
	v_add3_u32 v11, v11, v15, s75
	v_lshrrev_b32_e32 v8, 16, v8
	v_lshrrev_b32_e32 v10, 16, v10
	v_and_or_b32 v8, v9, s95, v8
	v_and_or_b32 v9, v11, s95, v10
	global_store_dwordx2 v[36:37], v[8:9], off offset:2560
	s_waitcnt vmcnt(1)
	v_pk_mul_f32 v[6:7], v[6:7], v[106:107]
	v_pk_mul_f32 v[4:5], v[4:5], v[104:105]
	v_pk_add_f32 v[8:9], v[138:139], 1.0 op_sel_hi:[1, 0]
	v_pk_add_f32 v[10:11], v[136:137], 1.0 op_sel_hi:[1, 0]
	v_pk_mul_f32 v[6:7], v[6:7], v[8:9]
	v_pk_mul_f32 v[4:5], v[4:5], v[10:11]
	v_bfe_u32 v10, v6, 16, 1
	v_bfe_u32 v8, v4, 16, 1
	v_bfe_u32 v9, v5, 16, 1
	v_bfe_u32 v11, v7, 16, 1
	v_add3_u32 v4, v4, v8, s75
	v_add3_u32 v6, v6, v10, s75
	v_add3_u32 v5, v5, v9, s75
	v_add3_u32 v7, v7, v11, s75
	v_lshrrev_b32_e32 v4, 16, v4
	v_lshrrev_b32_e32 v6, 16, v6
	v_and_or_b32 v4, v5, s95, v4
	v_and_or_b32 v5, v7, s95, v6
	global_store_dwordx2 v[36:37], v[4:5], off offset:3072
	s_waitcnt vmcnt(0)
	v_pk_mul_f32 v[2:3], v[2:3], v[110:111]
	v_pk_mul_f32 v[0:1], v[0:1], v[108:109]
	v_pk_add_f32 v[4:5], v[142:143], 1.0 op_sel_hi:[1, 0]
	v_pk_add_f32 v[6:7], v[140:141], 1.0 op_sel_hi:[1, 0]
	v_pk_mul_f32 v[2:3], v[2:3], v[4:5]
	v_pk_mul_f32 v[0:1], v[0:1], v[6:7]
	v_bfe_u32 v6, v2, 16, 1
	v_bfe_u32 v4, v0, 16, 1
	v_bfe_u32 v5, v1, 16, 1
	v_bfe_u32 v7, v3, 16, 1
	v_add3_u32 v0, v0, v4, s75
	v_add3_u32 v2, v2, v6, s75
	v_add3_u32 v1, v1, v5, s75
	v_add3_u32 v3, v3, v7, s75
	v_lshrrev_b32_e32 v0, 16, v0
	v_lshrrev_b32_e32 v2, 16, v2
	v_and_or_b32 v0, v1, s95, v0
	v_and_or_b32 v1, v3, s95, v2
	global_store_dwordx2 v[36:37], v[0:1], off offset:3584
	s_cbranch_scc0 .LBB0_41

; __device__ __forceinline__ unsigned pk2(float lo, float hi) { return f2bf(lo) | (f2bf(hi) << 16); }
; __device__ __forceinline__ void phase_xs(Ctx& F, const float* xlat, const float* xctx, const float* g, const float* modl, float* ss1, bf16* XS) {
;     ...
;         for (int q = 0; q < 2; ++q) { const int row = row0 + q; const int s = row < ML ? (row >> 13) : 4;
;             const float* sc = modl + s * MODW + DM;
; #pragma unroll
;             for (int j = 0; j < 4; ++j) ss[q] += (v[q][j][0] * v[q][j][0] + v[q][j][1] * v[q][j][1]) + (v[q][j][2] * v[q][j][2] + v[q][j][3] * v[q][j][3]);
;             ss[q] = wave_sum(ss[q]);
;             if (lane == 0) ss1[row] = ss[q];
; #pragma unroll
;             for (int j = 0; j < 4; ++j) { const int c = 256 * j + 4 * lane;
;                 const f32x4 gg = *(const f32x4*)(g + c), s1 = *(const f32x4*)(sc + c);
;                 const f32x4 y = v[q][j] * gg * (s1 + 1.0f);
;                 v2u w; w.x = pk2(y[0], y[1]); w.y = pk2(y[2], y[3]); *(v2u*)(XS + (size_t)row * DM + c) = w; } }
.LBB0_39:
	s_or_b64 exec, exec, s[14:15]
	s_ashr_i32 s20, s4, 13
	s_mulk_i32 s20, 0x1800
	s_and_b64 s[0:1], s[0:1], exec
	s_cselect_b32 s0, s20, 0x6000
	s_ashr_i32 s1, s0, 31
	s_lshl_b64 s[0:1], s[0:1], 2
	s_add_u32 s0, s62, s0
	s_addc_u32 s1, s63, s1
	s_add_u32 s14, s0, 0x1000
	s_addc_u32 s15, s1, 0
	global_load_dwordx4 v[96:99], v[32:33], off
	global_load_dwordx4 v[112:115], v44, s[14:15]
	global_load_dwordx4 v[100:103], v[32:33], off offset:1024
	global_load_dwordx4 v[116:119], v45, s[14:15]
	global_load_dwordx4 v[104:107], v[32:33], off offset:2048
	global_load_dwordx4 v[120:123], v46, s[14:15]
	global_load_dwordx4 v[108:111], v[32:33], off offset:3072
	global_load_dwordx4 v[124:127], v47, s[14:15]
	s_waitcnt lgkmcnt(0)
	v_lshl_add_u64 v[36:37], s[62:63], 0, v[34:35]
	s_mov_b32 s0, 0x3400000
	v_add_co_u32_e64 v36, s[0:1], s0, v36
	s_waitcnt vmcnt(6)
	v_pk_mul_f32 v[30:31], v[30:31], v[98:99]
	v_pk_mul_f32 v[28:29], v[28:29], v[96:97]
	v_pk_add_f32 v[48:49], v[114:115], 1.0 op_sel_hi:[1, 0]
	v_pk_add_f32 v[50:51], v[112:113], 1.0 op_sel_hi:[1, 0]
	v_pk_mul_f32 v[30:31], v[30:31], v[48:49]
	v_pk_mul_f32 v[28:29], v[28:29], v[50:51]
	v_bfe_u32 v50, v30, 16, 1
	v_bfe_u32 v48, v28, 16, 1
	v_bfe_u32 v49, v29, 16, 1
	v_bfe_u32 v51, v31, 16, 1
	v_add3_u32 v28, v28, v48, s75
	v_add3_u32 v30, v30, v50, s75
	v_add3_u32 v29, v29, v49, s75
	v_add3_u32 v31, v31, v51, s75
	v_lshrrev_b32_e32 v28, 16, v28
	v_lshrrev_b32_e32 v30, 16, v30
	v_addc_co_u32_e64 v37, s[0:1], 0, v37, s[0:1]
	v_and_or_b32 v28, v29, s95, v28
	v_and_or_b32 v29, v31, s95, v30
	global_store_dwordx2 v[36:37], v[28:29], off
	s_waitcnt vmcnt(4)
	v_pk_mul_f32 v[26:27], v[26:27], v[102:103]
	v_pk_mul_f32 v[24:25], v[24:25], v[100:101]
	v_pk_add_f32 v[28:29], v[118:119], 1.0 op_sel_hi:[1, 0]
	v_pk_add_f32 v[30:31], v[116:117], 1.0 op_sel_hi:[1, 0]
	v_pk_mul_f32 v[26:27], v[26:27], v[28:29]
	v_pk_mul_f32 v[24:25], v[24:25], v[30:31]
	v_bfe_u32 v30, v26, 16, 1
	v_bfe_u32 v28, v24, 16, 1
	v_bfe_u32 v29, v25, 16, 1
	v_bfe_u32 v31, v27, 16, 1
	v_add3_u32 v24, v24, v28, s75
	v_add3_u32 v26, v26, v30, s75
	v_add3_u32 v25, v25, v29, s75
	v_add3_u32 v27, v27, v31, s75
	v_lshrrev_b32_e32 v24, 16, v24
	v_lshrrev_b32_e32 v26, 16, v26
	v_and_or_b32 v24, v25, s95, v24
	v_and_or_b32 v25, v27, s95, v26
	global_store_dwordx2 v[36:37], v[24:25], off offset:512
	v_mul_f32_e32 v48, v5, v5
	v_mul_f32_e32 v49, v7, v7
	v_mul_f32_e32 v50, v1, v1
	v_mul_f32_e32 v51, v3, v3
	v_fmac_f32_e32 v48, v4, v4
	v_fmac_f32_e32 v49, v6, v6
	v_fmac_f32_e32 v50, v0, v0
	v_fmac_f32_e32 v51, v2, v2
	s_waitcnt vmcnt(2)
	v_pk_mul_f32 v[22:23], v[22:23], v[106:107]
	v_pk_mul_f32 v[20:21], v[20:21], v[104:105]
	v_pk_add_f32 v[24:25], v[122:123], 1.0 op_sel_hi:[1, 0]
	v_pk_add_f32 v[26:27], v[120:121], 1.0 op_sel_hi:[1, 0]
	v_pk_mul_f32 v[22:23], v[22:23], v[24:25]
	v_pk_mul_f32 v[20:21], v[20:21], v[26:27]
	v_bfe_u32 v26, v22, 16, 1
	v_bfe_u32 v24, v20, 16, 1
	v_bfe_u32 v25, v21, 16, 1
	v_bfe_u32 v27, v23, 16, 1
	v_add3_u32 v20, v20, v24, s75
	v_add3_u32 v22, v22, v26, s75
	v_add3_u32 v21, v21, v25, s75
	v_add3_u32 v23, v23, v27, s75
	v_lshrrev_b32_e32 v20, 16, v20
	v_lshrrev_b32_e32 v22, 16, v22
	v_and_or_b32 v20, v21, s95, v20
	v_and_or_b32 v21, v23, s95, v22
	global_store_dwordx2 v[36:37], v[20:21], off offset:1024
	v_mul_f32_e32 v20, v13, v13
	v_mul_f32_e32 v21, v15, v15
	v_mul_f32_e32 v30, v9, v9
	v_mul_f32_e32 v31, v11, v11
	v_fmac_f32_e32 v20, v12, v12
	v_fmac_f32_e32 v21, v14, v14
	v_fmac_f32_e32 v30, v8, v8
	v_fmac_f32_e32 v31, v10, v10
	v_add_f32_e32 v20, v20, v21
	v_add_f32_e32 v21, v30, v31
	v_add_f32_e32 v30, v48, v49
	v_add_f32_e32 v20, v20, v21
	v_add_f32_e32 v31, v50, v51
	v_add_f32_e32 v20, v20, v30
	v_add_f32_e32 v20, v20, v31
	ds_bpermute_b32 v21, v38, v20
	s_waitcnt lgkmcnt(0)
	v_add_f32_e32 v20, v20, v21
	ds_bpermute_b32 v21, v39, v20
	s_waitcnt lgkmcnt(0)
	v_add_f32_e32 v20, v20, v21
	ds_bpermute_b32 v21, v40, v20
	s_waitcnt lgkmcnt(0)
	v_add_f32_e32 v20, v20, v21
	ds_bpermute_b32 v21, v41, v20
	s_waitcnt lgkmcnt(0)
	v_add_f32_e32 v20, v20, v21
	ds_bpermute_b32 v21, v42, v20
	s_waitcnt lgkmcnt(0)
	v_add_f32_e32 v20, v20, v21
	ds_bpermute_b32 v21, v43, v20
	s_waitcnt vmcnt(0)
	v_pk_mul_f32 v[18:19], v[18:19], v[110:111]
	v_pk_mul_f32 v[16:17], v[16:17], v[108:109]
	v_pk_add_f32 v[22:23], v[126:127], 1.0 op_sel_hi:[1, 0]
	v_pk_add_f32 v[24:25], v[124:125], 1.0 op_sel_hi:[1, 0]
	v_pk_mul_f32 v[18:19], v[18:19], v[22:23]
	v_pk_mul_f32 v[16:17], v[16:17], v[24:25]
	v_bfe_u32 v24, v18, 16, 1
	v_bfe_u32 v22, v16, 16, 1
	v_bfe_u32 v23, v17, 16, 1
	v_bfe_u32 v25, v19, 16, 1
	v_add3_u32 v16, v16, v22, s75
	v_add3_u32 v18, v18, v24, s75
	v_add3_u32 v17, v17, v23, s75
	v_add3_u32 v19, v19, v25, s75
	v_lshrrev_b32_e32 v16, 16, v16
	v_lshrrev_b32_e32 v18, 16, v18
	v_and_or_b32 v16, v17, s95, v16
	v_and_or_b32 v17, v19, s95, v18
	global_store_dwordx2 v[36:37], v[16:17], off offset:1536
	s_and_saveexec_b64 s[0:1], vcc
	s_cbranch_execz .LBB0_36
	s_add_u32 s14, s62, s6
	s_waitcnt lgkmcnt(0)
	v_add_f32_e32 v16, v20, v21
	s_addc_u32 s15, s63, s7
	global_store_dword v245, v16, s[14:15] offset:4
	s_branch .LBB0_36
